# c4 + attention counted lgkmcnt waits: PV groups wait per MFMA, QK next-fragment read issued one MFMA earlier
# speedup vs baseline: 1.0023x; 1.0023x over previous
; DEVI void finishSM(f32x16& p0, f32x16& p1, float alpha, float& l_reg, bf16x8& pa0, bf16x8& pa1, bf16x8& pa2, bf16x8& pa3) {
;     for (int r = 0; r < 16; ++r) p1[r] = __builtin_amdgcn_exp2f(p1[r]);
;     float ps = 0; for (int r = 0; r < 16; ++r) ps += p0[r]; for (int r = 0; r < 16; ++r) ps += p1[r];
;     { auto rr = __builtin_amdgcn_permlane32_swap(__float_as_uint(ps), __float_as_uint(ps), false, false);
;       ps = __uint_as_float(rr[0]) + __uint_as_float(rr[1]); }
;     l_reg = l_reg * alpha + ps;
;     ...
;     PK4(p0, 0, pa0); PK4(p0, 8, pa1); PK4(p1, 0, pa2); PK4(p1, 8, pa3);
;     ...
; }
; template <int KB>
; DEVI void qkt(f32x16& p0, f32x16& p1, const char* K_lds, const char* biasb0, int r32, int hi, const bf16x8* qr) {
;     int hb_ = hi * 16; asm volatile("" : "+v"(hb_)); const char* biasb = biasb0 + hb_;
; #pragma unroll
;     for (int g = 0; g < 4; ++g) { const f32x4 b0 = *(const f32x4*)(biasb + KB * 256 + g * 32), b1 = *(const f32x4*)(biasb + KB * 256 + 128 + g * 32);
; #pragma unroll
;         for (int i = 0; i < 4; ++i) { p0[4 * g + i] = b0[i]; p1[4 * g + i] = b1[i]; } }
;     const char* kb[4];
; #pragma unroll
;     for (int dd = 0; dd < 4; ++dd) kb[dd] = K_lds + KB * SHM_K + KSWZ(r32, (dd * 16 + hi * 8) * 2);
; #pragma unroll
;     for (int d0 = 0; d0 < 8; ++d0) { const char* a = kb[d0 & 3] + (d0 >> 2) * 128;
;         bf16x8 b0 = *reinterpret_cast<const bf16x8*>(a);
;         bf16x8 b1 = *reinterpret_cast<const bf16x8*>(a + 32 * 256);
;         p0 = __builtin_amdgcn_mfma_f32_32x32x16_bf16(b0, qr[d0], p0, 0, 0, 0);
;         p1 = __builtin_amdgcn_mfma_f32_32x32x16_bf16(b1, qr[d0], p1, 0, 0, 0); }
; }
.LBB0_215:
	v_mov_b32_e32 v2, v200
	s_add_i32 s6, 0, 0x10800
	v_add_u32_e32 v2, s6, v2
	ds_read_b128 v[100:103], v2 offset:256
	ds_read_b128 v[104:107], v2 offset:288
	ds_read_b128 v[84:87], v2 offset:384
	ds_read_b128 v[88:91], v2 offset:416
	ds_read_b128 v[108:111], v2 offset:320
	ds_read_b128 v[92:95], v2 offset:448
	ds_read_b128 v[112:115], v2 offset:352
	ds_read_b128 v[96:99], v2 offset:480
	ds_read_b128 v[2:5], v233 offset:49152
	ds_read_b128 v[6:9], v233 offset:57344
	v_add_f32_e32 v80, 0, v190
	v_add_f32_e32 v80, v192, v80
	s_waitcnt lgkmcnt(1)
	s_waitcnt lgkmcnt(1)
	v_mfma_f32_32x32x16_bf16 v[100:115], v[2:5], v[172:175], v[100:115]
	ds_read_b128 v[2:5], v234 offset:49152
	v_add_f32_e32 v80, v188, v80
	v_add_f32_e32 v80, v191, v80
	v_add_f32_e32 v80, v187, v80
	v_add_f32_e32 v80, v189, v80
	v_add_f32_e32 v80, v185, v80
	v_add_f32_e32 v80, v186, v80
	v_add_f32_e32 v80, v181, v80
	s_waitcnt lgkmcnt(1)
	v_mfma_f32_32x32x16_bf16 v[84:99], v[6:9], v[172:175], v[84:99]
	ds_read_b128 v[6:9], v234 offset:57344
	v_add_f32_e32 v80, v184, v80
	v_add_f32_e32 v80, v178, v80
	v_add_f32_e32 v80, v182, v80
	v_add_f32_e32 v80, v176, v80
	v_add_f32_e32 v80, v183, v80
	v_add_f32_e32 v80, v177, v80
	s_waitcnt lgkmcnt(1)
	v_mfma_f32_32x32x16_bf16 v[100:115], v[2:5], v[168:171], v[100:115]
	ds_read_b128 v[2:5], v232 offset:49152
	v_add_f32_e32 v80, v179, v80
	v_exp_f32_e32 v10, v134
	v_exp_f32_e32 v11, v135
	v_exp_f32_e32 v12, v132
	v_exp_f32_e32 v13, v133
	v_exp_f32_e32 v126, v130
	v_exp_f32_e32 v127, v131
	s_waitcnt lgkmcnt(1)
	v_mfma_f32_32x32x16_bf16 v[84:99], v[6:9], v[168:171], v[84:99]
	ds_read_b128 v[6:9], v232 offset:57344
	v_exp_f32_e32 v128, v128
	v_exp_f32_e32 v129, v129
	s_waitcnt lgkmcnt(1)
	v_mfma_f32_32x32x16_bf16 v[100:115], v[2:5], v[164:167], v[100:115]
	ds_read_b128 v[2:5], v230 offset:49152
	s_waitcnt lgkmcnt(1)
	v_mfma_f32_32x32x16_bf16 v[84:99], v[6:9], v[164:167], v[84:99]
	ds_read_b128 v[6:9], v230 offset:57344
	s_waitcnt lgkmcnt(1)
	v_mfma_f32_32x32x16_bf16 v[100:115], v[2:5], v[160:163], v[100:115]
	ds_read_b128 v[2:5], v233 offset:49280
	s_waitcnt lgkmcnt(1)
	v_mfma_f32_32x32x16_bf16 v[84:99], v[6:9], v[160:163], v[84:99]
	ds_read_b128 v[6:9], v233 offset:57472
	s_waitcnt lgkmcnt(1)
	v_mfma_f32_32x32x16_bf16 v[100:115], v[2:5], v[156:159], v[100:115]
	ds_read_b128 v[2:5], v234 offset:49280
	s_waitcnt lgkmcnt(1)
	v_mfma_f32_32x32x16_bf16 v[84:99], v[6:9], v[156:159], v[84:99]
	ds_read_b128 v[6:9], v234 offset:57472
	s_waitcnt lgkmcnt(1)
	v_mfma_f32_32x32x16_bf16 v[100:115], v[2:5], v[152:155], v[100:115]
	ds_read_b128 v[2:5], v232 offset:49280
	s_waitcnt lgkmcnt(1)
	v_mfma_f32_32x32x16_bf16 v[84:99], v[6:9], v[152:155], v[84:99]
	ds_read_b128 v[6:9], v232 offset:57472
	s_waitcnt lgkmcnt(1)
	v_mfma_f32_32x32x16_bf16 v[100:115], v[2:5], v[148:151], v[100:115]
	ds_read_b128 v[2:5], v230 offset:49280
	s_waitcnt lgkmcnt(1)
	v_mfma_f32_32x32x16_bf16 v[84:99], v[6:9], v[148:151], v[84:99]
	ds_read_b128 v[6:9], v230 offset:57472
	s_waitcnt lgkmcnt(1)
	v_mfma_f32_32x32x16_bf16 v[100:115], v[2:5], v[144:147], v[100:115]
	v_exp_f32_e32 v2, v142
	v_exp_f32_e32 v3, v143
	v_exp_f32_e32 v4, v140
	v_exp_f32_e32 v5, v141
	v_add_f32_e32 v80, v2, v80
	v_add_f32_e32 v80, v3, v80
	v_add_f32_e32 v80, v4, v80
	s_waitcnt lgkmcnt(0)
	v_mfma_f32_32x32x16_bf16 v[84:99], v[6:9], v[144:147], v[84:99]
	v_exp_f32_e32 v6, v138
	v_exp_f32_e32 v7, v139
	v_exp_f32_e32 v8, v136
	v_exp_f32_e32 v9, v137
	v_add_f32_e32 v80, v5, v80
	v_add_f32_e32 v80, v6, v80
	v_add_f32_e32 v80, v7, v80
	v_add_f32_e32 v80, v8, v80
	v_add_f32_e32 v80, v9, v80
	v_add_f32_e32 v80, v10, v80
	v_add_f32_e32 v80, v11, v80
	v_add_f32_e32 v80, v12, v80
	v_add_f32_e32 v80, v13, v80
	v_add_f32_e32 v80, v126, v80
	v_add_f32_e32 v80, v127, v80
	v_add_f32_e32 v80, v128, v80
	v_add_f32_e32 v205, v129, v80
	v_mov_b32_e32 v239, v205
	v_cvt_pk_bf16_f32 v80, v190, v192
	v_cvt_pk_bf16_f32 v81, v188, v191
	v_cvt_pk_bf16_f32 v82, v187, v189
	v_cvt_pk_bf16_f32 v83, v185, v186
	v_cvt_pk_bf16_f32 v116, v181, v184
	v_cvt_pk_bf16_f32 v117, v178, v182
	v_cvt_pk_bf16_f32 v118, v176, v183
	v_cvt_pk_bf16_f32 v119, v177, v179
	v_cvt_pk_bf16_f32 v120, v2, v3
	v_cvt_pk_bf16_f32 v121, v4, v5
	v_cvt_pk_bf16_f32 v122, v6, v7
	v_cvt_pk_bf16_f32 v123, v8, v9
	v_cvt_pk_bf16_f32 v124, v10, v11
	v_cvt_pk_bf16_f32 v125, v12, v13
	v_cvt_pk_bf16_f32 v126, v126, v127
	v_cvt_pk_bf16_f32 v127, v128, v129
	s_nop 1
	v_permlane32_swap_b32_e32 v205, v239
	v_permlane32_swap_b32_e32 v80, v82
	v_permlane32_swap_b32_e32 v81, v83
	v_permlane32_swap_b32_e32 v116, v118
	v_permlane32_swap_b32_e32 v117, v119
	v_permlane32_swap_b32_e32 v120, v122
	v_permlane32_swap_b32_e32 v121, v123
	v_permlane32_swap_b32_e32 v124, v126
	v_permlane32_swap_b32_e32 v125, v127
	v_add_u32_e32 v210, s90, v201
	v_add_u32_e32 v2, 64, v210
	v_add_u32_e32 v4, 0x60, v210
	v_ashrrev_i32_e32 v3, 31, v2
	v_ashrrev_i32_e32 v5, 31, v4
	v_lshlrev_b64 v[10:11], 11, v[2:3]
	v_lshlrev_b64 v[12:13], 11, v[4:5]
	v_lshl_add_u64 v[2:3], v[14:15], 0, v[10:11]
	v_lshl_add_u64 v[6:7], v[14:15], 0, v[12:13]
	v_lshl_add_u64 v[10:11], v[206:207], 0, v[10:11]
	flat_load_dwordx4 v[2:5], v[2:3]
	s_nop 0
	flat_load_dwordx4 v[6:9], v[6:7]
	v_lshl_add_u64 v[128:129], v[206:207], 0, v[12:13]
	flat_load_dwordx4 v[10:13], v[10:11]
	s_nop 0
	flat_load_dwordx4 v[176:179], v[128:129]
	v_cndmask_b32_e64 v128, 0, 1, s[94:95]
	v_cmp_ne_u32_e64 s[6:7], 1, v128
	s_andn2_b64 vcc, exec, s[94:95]
	s_cbranch_vccnz .LBB0_217
	s_add_i32 s8, s90, 64
	s_ashr_i32 s9, s8, 31
	v_lshl_add_u64 v[128:129], s[8:9], 2, v[208:209]
	s_mov_b64 s[8:9], src_shared_base
	s_cmp_lg_u32 0, -1
	s_cselect_b32 s8, 0, 0
	s_cselect_b32 s9, s9, 0
	s_add_u32 s8, s8, 0x10800
	s_addc_u32 s9, s9, 0
	s_cmp_lg_u64 s[8:9], 0
	s_cselect_b32 m0, s8, -1
	s_nop 0
	global_load_lds_dword v[128:129], off
; DEVI void mask_tile(f32x16& p0, f32x16& p1, int dq, unsigned W) {
;     const float NEG = -__builtin_inff();
; #pragma unroll
;     for (int r = 0; r < 16; ++r) {
;         const int c = (r & 3) + 8 * (r >> 2);
;         if ((unsigned)(dq - c) >= W) p0[r] = NEG;
;         if ((unsigned)(dq - c - 32) >= W) p1[r] = NEG;
;     }
; }
; template <int VB>
; DEVI void pv_tile(f32x16* o, int vb0, bf16x8 pa0, bf16x8 pa1, bf16x8 pa2, bf16x8 pa3) {
;     ...
;     PV_D0(0); PV_D0(1); PV_D0(2); PV_D0(3);
.LBB0_217:
	ds_read_b64_tr_b16 v[128:129], v227 offset:0
	ds_read_b64_tr_b16 v[130:131], v227 offset:0x800
	ds_read_b64_tr_b16 v[132:133], v227 offset:0x1000
	ds_read_b64_tr_b16 v[134:135], v227 offset:0x1800
	ds_read_b64_tr_b16 v[136:137], v227 offset:0x2000
	ds_read_b64_tr_b16 v[138:139], v227 offset:0x2800
	ds_read_b64_tr_b16 v[140:141], v227 offset:0x3000
	ds_read_b64_tr_b16 v[142:143], v227 offset:0x3800
	s_nop 0
	s_nop 0
	s_waitcnt lgkmcnt(6)
	v_mfma_f32_32x32x16_bf16 v[64:79], v[80:83], v[128:131], v[64:79]
	ds_read_b64_tr_b16 v[128:129], v227 offset:0x200
	ds_read_b64_tr_b16 v[130:131], v227 offset:0xa00
	s_waitcnt lgkmcnt(6)
	v_mfma_f32_32x32x16_bf16 v[64:79], v[116:119], v[132:135], v[64:79]
	ds_read_b64_tr_b16 v[132:133], v227 offset:0x1200
	ds_read_b64_tr_b16 v[134:135], v227 offset:0x1a00
	s_waitcnt lgkmcnt(6)
	v_mfma_f32_32x32x16_bf16 v[64:79], v[120:123], v[136:139], v[64:79]
	ds_read_b64_tr_b16 v[136:137], v227 offset:0x2200
	ds_read_b64_tr_b16 v[138:139], v227 offset:0x2a00
	s_waitcnt lgkmcnt(6)
	v_mfma_f32_32x32x16_bf16 v[64:79], v[124:127], v[140:143], v[64:79]
	ds_read_b64_tr_b16 v[140:141], v227 offset:0x3200
	ds_read_b64_tr_b16 v[142:143], v227 offset:0x3a00
	s_nop 0
	s_waitcnt lgkmcnt(6)
	v_mfma_f32_32x32x16_bf16 v[48:63], v[80:83], v[128:131], v[48:63]
	ds_read_b64_tr_b16 v[128:129], v227 offset:0x400
	ds_read_b64_tr_b16 v[130:131], v227 offset:0xc00
	s_waitcnt lgkmcnt(6)
	v_mfma_f32_32x32x16_bf16 v[48:63], v[116:119], v[132:135], v[48:63]
	ds_read_b64_tr_b16 v[132:133], v227 offset:0x1400
	ds_read_b64_tr_b16 v[134:135], v227 offset:0x1c00
	s_waitcnt lgkmcnt(6)
	v_mfma_f32_32x32x16_bf16 v[48:63], v[120:123], v[136:139], v[48:63]
	ds_read_b64_tr_b16 v[136:137], v227 offset:0x2400
	ds_read_b64_tr_b16 v[138:139], v227 offset:0x2c00
	s_waitcnt lgkmcnt(6)
	v_mfma_f32_32x32x16_bf16 v[48:63], v[124:127], v[140:143], v[48:63]
	ds_read_b64_tr_b16 v[140:141], v227 offset:0x3400
	ds_read_b64_tr_b16 v[142:143], v227 offset:0x3c00
	s_nop 0
	s_waitcnt lgkmcnt(6)
	v_mfma_f32_32x32x16_bf16 v[32:47], v[80:83], v[128:131], v[32:47]
	ds_read_b64_tr_b16 v[128:129], v227 offset:0x600
	ds_read_b64_tr_b16 v[130:131], v227 offset:0xe00
	s_waitcnt lgkmcnt(6)
	v_mfma_f32_32x32x16_bf16 v[32:47], v[116:119], v[132:135], v[32:47]
	ds_read_b64_tr_b16 v[132:133], v227 offset:0x1600
	ds_read_b64_tr_b16 v[134:135], v227 offset:0x1e00
	s_waitcnt lgkmcnt(6)
	v_mfma_f32_32x32x16_bf16 v[32:47], v[120:123], v[136:139], v[32:47]
	ds_read_b64_tr_b16 v[136:137], v227 offset:0x2600
	ds_read_b64_tr_b16 v[138:139], v227 offset:0x2e00
	s_waitcnt lgkmcnt(6)
	v_mfma_f32_32x32x16_bf16 v[32:47], v[124:127], v[140:143], v[32:47]
	ds_read_b64_tr_b16 v[140:141], v227 offset:0x3600
	ds_read_b64_tr_b16 v[142:143], v227 offset:0x3e00
	s_nop 0
	s_waitcnt lgkmcnt(6)
	v_mfma_f32_32x32x16_bf16 v[16:31], v[80:83], v[128:131], v[16:31]
	s_add_i32 s8, s90, 0xbf
	s_cmp_le_i32 s8, s11
	s_waitcnt lgkmcnt(4)
	v_mfma_f32_32x32x16_bf16 v[16:31], v[116:119], v[132:135], v[16:31]
	s_waitcnt lgkmcnt(2)
	v_mfma_f32_32x32x16_bf16 v[16:31], v[120:123], v[136:139], v[16:31]
	s_waitcnt lgkmcnt(0)
	v_mfma_f32_32x32x16_bf16 v[16:31], v[124:127], v[140:143], v[16:31]
	s_cbranch_scc1 .LBB0_219
	v_add_u32_e32 v80, 0x4000003b, v203
	v_cmp_gt_u32_e32 vcc, 2.0, v80
	v_add_u32_e32 v80, 27, v203
	s_nop 0
	v_cndmask_b32_e32 v100, v254, v100, vcc
	v_cmp_lt_u32_e32 vcc, s55, v80
	v_add_u32_e32 v80, 58, v203
	s_nop 0
	v_cndmask_b32_e32 v84, v254, v84, vcc
	v_cmp_lt_u32_e32 vcc, s55, v80
	v_add_u32_e32 v80, 26, v203
	s_nop 0
	v_cndmask_b32_e32 v101, v254, v101, vcc
	v_cmp_lt_u32_e32 vcc, s55, v80
	v_add_u32_e32 v80, 57, v203
	s_nop 0
	v_cndmask_b32_e32 v85, v254, v85, vcc
	v_cmp_lt_u32_e32 vcc, s55, v80
	v_add_u32_e32 v80, 25, v203
	s_nop 0
	v_cndmask_b32_e32 v102, v254, v102, vcc
	v_cmp_lt_u32_e32 vcc, s55, v80
	v_add_u32_e32 v80, 56, v203
	s_nop 0
	v_cndmask_b32_e32 v86, v254, v86, vcc
	v_cmp_lt_u32_e32 vcc, s55, v80
	v_add_u32_e32 v80, 24, v203
	s_nop 0
	v_cndmask_b32_e32 v103, v254, v103, vcc
	v_cmp_lt_u32_e32 vcc, s55, v80
	v_add_u32_e32 v80, 51, v203
	s_nop 0
	v_cndmask_b32_e32 v87, v254, v87, vcc
	v_cmp_lt_u32_e32 vcc, s55, v80
	v_add_u32_e32 v80, 19, v203
	s_nop 0
	v_cndmask_b32_e32 v104, v254, v104, vcc
	v_cmp_lt_u32_e32 vcc, s55, v80
	v_add_u32_e32 v80, 50, v203
	s_nop 0
	v_cndmask_b32_e32 v88, v254, v88, vcc
	v_cmp_lt_u32_e32 vcc, s55, v80
	v_add_u32_e32 v80, 18, v203
	s_nop 0
	v_cndmask_b32_e32 v105, v254, v105, vcc
	v_cmp_lt_u32_e32 vcc, s55, v80
	v_add_u32_e32 v80, 49, v203
	s_nop 0
	v_cndmask_b32_e32 v89, v254, v89, vcc
	v_cmp_lt_u32_e32 vcc, s55, v80
	v_add_u32_e32 v80, 17, v203
	s_nop 0
	v_cndmask_b32_e32 v106, v254, v106, vcc
	v_cmp_lt_u32_e32 vcc, s55, v80
	v_add_u32_e32 v80, 48, v203
	s_nop 0
	v_cndmask_b32_e32 v90, v254, v90, vcc
	v_cmp_lt_u32_e32 vcc, s55, v80
	v_add_u32_e32 v80, 16, v203
	s_nop 0
	v_cndmask_b32_e32 v107, v254, v107, vcc
	v_cmp_lt_u32_e32 vcc, s55, v80
	v_add_u32_e32 v80, 43, v203
	s_nop 0
	v_cndmask_b32_e32 v91, v254, v91, vcc
	v_cmp_lt_u32_e32 vcc, s55, v80
	v_add_u32_e32 v80, 11, v203
	s_nop 0
	v_cndmask_b32_e32 v108, v254, v108, vcc
	v_cmp_lt_u32_e32 vcc, s55, v80
	v_add_u32_e32 v80, 42, v203
	s_nop 0
	v_cndmask_b32_e32 v92, v254, v92, vcc
	v_cmp_lt_u32_e32 vcc, s55, v80
	v_add_u32_e32 v80, 10, v203
	s_nop 0
	v_cndmask_b32_e32 v109, v254, v109, vcc
	v_cmp_lt_u32_e32 vcc, s55, v80
	v_add_u32_e32 v80, 41, v203
	s_nop 0
	v_cndmask_b32_e32 v93, v254, v93, vcc
	v_cmp_lt_u32_e32 vcc, s55, v80
	v_add_u32_e32 v80, 9, v203
	s_nop 0
	v_cndmask_b32_e32 v110, v254, v110, vcc
	v_cmp_lt_u32_e32 vcc, s55, v80
	v_add_u32_e32 v80, 40, v203
	s_nop 0
	v_cndmask_b32_e32 v94, v254, v94, vcc
	v_cmp_lt_u32_e32 vcc, s55, v80
	v_add_u32_e32 v80, 8, v203
	s_nop 0
	v_cndmask_b32_e32 v111, v254, v111, vcc
	v_cmp_lt_u32_e32 vcc, s55, v80
	v_add_u32_e32 v80, 35, v203
	s_nop 0
	v_cndmask_b32_e32 v95, v254, v95, vcc
	v_cmp_lt_u32_e32 vcc, s55, v80
	v_add_u32_e32 v80, 3, v203
	s_nop 0
	v_cndmask_b32_e32 v112, v254, v112, vcc
	v_cmp_lt_u32_e32 vcc, s55, v80
	v_add_u32_e32 v80, 34, v203
	s_nop 0
	v_cndmask_b32_e32 v96, v254, v96, vcc
	v_cmp_lt_u32_e32 vcc, s55, v80
	v_add_u32_e32 v80, 2, v203
	s_nop 0
	v_cndmask_b32_e32 v113, v254, v113, vcc
	v_cmp_lt_u32_e32 vcc, s55, v80
	v_add_u32_e32 v80, 33, v203
	s_nop 0
	v_cndmask_b32_e32 v97, v254, v97, vcc
	v_cmp_lt_u32_e32 vcc, s55, v80
	v_add_u32_e32 v80, 1, v203
	s_nop 0
	v_cndmask_b32_e32 v114, v254, v114, vcc
	v_cmp_lt_u32_e32 vcc, s55, v80
	v_add_u32_e32 v80, 32, v203
	s_nop 0
	v_cndmask_b32_e32 v98, v254, v98, vcc
	v_cmp_lt_u32_e32 vcc, s55, v80
	s_nop 1
	v_cndmask_b32_e32 v115, v254, v115, vcc
	v_cmp_lt_u32_e32 vcc, s55, v203
	s_nop 1
	v_cndmask_b32_e32 v99, v254, v99, vcc

; DEVI void partialSM(f32x16& p0, f32x16& p1, float& m_reg, float& mn, float& alpha) {
;     float pmax = p0[0]; for (int r = 1; r < 16; ++r) pmax = fmaxf(pmax, p0[r]); for (int r = 0; r < 16; ++r) pmax = fmaxf(pmax, p1[r]);
;     { auto rr = __builtin_amdgcn_permlane32_swap(__float_as_uint(pmax), __float_as_uint(pmax), false, false);
;       pmax = fmaxf(__uint_as_float(rr[0]), __uint_as_float(rr[1])); }
;     constexpr float C2 = 1.4426950408889634f * SCALE;
;     if (__builtin_expect(__all((pmax - m_reg) * SCALE <= THR), 1)) { mn = m_reg; alpha = 1.f; }
;     else { mn = fmaxf(m_reg, pmax); alpha = __builtin_amdgcn_exp2f((m_reg - mn) * C2); m_reg = mn; }
;     const float mnL = -mn * C2;
;     for (int r = 0; r < 16; ++r) p0[r] = fmaf(p0[r], C2, mnL); for (int r = 0; r < 16; ++r) p1[r] = fmaf(p1[r], C2, mnL);
;     for (int r = 0; r < 16; ++r) p0[r] = __builtin_amdgcn_exp2f(p0[r]);
; }
; DEVI void finishSM(f32x16& p0, f32x16& p1, float alpha, float& l_reg, bf16x8& pa0, bf16x8& pa1, bf16x8& pa2, bf16x8& pa3) {
;     for (int r = 0; r < 16; ++r) p1[r] = __builtin_amdgcn_exp2f(p1[r]);
;     float ps = 0; for (int r = 0; r < 16; ++r) ps += p0[r]; for (int r = 0; r < 16; ++r) ps += p1[r];
;     { auto rr = __builtin_amdgcn_permlane32_swap(__float_as_uint(ps), __float_as_uint(ps), false, false);
;       ps = __uint_as_float(rr[0]) + __uint_as_float(rr[1]); }
;     l_reg = l_reg * alpha + ps;
;     ...
;     PK4(p0, 0, pa0); PK4(p0, 8, pa1); PK4(p1, 0, pa2); PK4(p1, 8, pa3);
;     ...
; }
; template <int KB>
; DEVI void qkt(f32x16& p0, f32x16& p1, const char* K_lds, const char* biasb0, int r32, int hi, const bf16x8* qr) {
;     int hb_ = hi * 16; asm volatile("" : "+v"(hb_)); const char* biasb = biasb0 + hb_;
; #pragma unroll
;     for (int g = 0; g < 4; ++g) { const f32x4 b0 = *(const f32x4*)(biasb + KB * 256 + g * 32), b1 = *(const f32x4*)(biasb + KB * 256 + 128 + g * 32);
; #pragma unroll
;         for (int i = 0; i < 4; ++i) { p0[4 * g + i] = b0[i]; p1[4 * g + i] = b1[i]; } }
;     const char* kb[4];
; #pragma unroll
;     for (int dd = 0; dd < 4; ++dd) kb[dd] = K_lds + KB * SHM_K + KSWZ(r32, (dd * 16 + hi * 8) * 2);
; #pragma unroll
;     for (int d0 = 0; d0 < 8; ++d0) { const char* a = kb[d0 & 3] + (d0 >> 2) * 128;
;         bf16x8 b0 = *reinterpret_cast<const bf16x8*>(a);
;         bf16x8 b1 = *reinterpret_cast<const bf16x8*>(a + 32 * 256);
.LBB0_223:
	v_cndmask_b32_e64 v241, v80, v180, s[8:9]
	v_mul_f32_e32 v180, 0xbe0293ee, v241
	v_fmamk_f32 v80, v100, 0x3e0293ee, v180
	v_fmamk_f32 v81, v101, 0x3e0293ee, v180
	v_fmamk_f32 v82, v102, 0x3e0293ee, v180
	v_fmamk_f32 v83, v103, 0x3e0293ee, v180
	v_fmamk_f32 v116, v104, 0x3e0293ee, v180
	v_fmamk_f32 v117, v105, 0x3e0293ee, v180
	v_fmamk_f32 v118, v106, 0x3e0293ee, v180
	v_fmamk_f32 v119, v107, 0x3e0293ee, v180
	v_fmamk_f32 v120, v108, 0x3e0293ee, v180
	v_fmamk_f32 v121, v109, 0x3e0293ee, v180
	v_fmamk_f32 v122, v110, 0x3e0293ee, v180
	v_fmamk_f32 v123, v111, 0x3e0293ee, v180
	v_fmamk_f32 v112, v112, 0x3e0293ee, v180
	v_fmamk_f32 v113, v113, 0x3e0293ee, v180
	v_fmamk_f32 v114, v114, 0x3e0293ee, v180
	v_fmamk_f32 v115, v115, 0x3e0293ee, v180
	v_fmamk_f32 v100, v84, 0x3e0293ee, v180
	v_fmamk_f32 v109, v85, 0x3e0293ee, v180
	v_fmamk_f32 v110, v86, 0x3e0293ee, v180
	v_fmamk_f32 v111, v87, 0x3e0293ee, v180
	v_fmamk_f32 v181, v88, 0x3e0293ee, v180
	v_fmamk_f32 v101, v89, 0x3e0293ee, v180
	v_fmamk_f32 v102, v90, 0x3e0293ee, v180
	v_fmamk_f32 v103, v91, 0x3e0293ee, v180
	v_fmamk_f32 v104, v92, 0x3e0293ee, v180
	v_fmamk_f32 v105, v93, 0x3e0293ee, v180
	v_fmamk_f32 v106, v94, 0x3e0293ee, v180
	v_fmamk_f32 v107, v95, 0x3e0293ee, v180
	v_exp_f32_e32 v80, v80
	v_exp_f32_e32 v81, v81
	v_exp_f32_e32 v82, v82
	v_exp_f32_e32 v83, v83
	v_exp_f32_e32 v84, v116
	v_exp_f32_e32 v85, v117
	v_exp_f32_e32 v86, v118
	v_exp_f32_e32 v87, v119
	v_exp_f32_e32 v88, v120
	v_exp_f32_e32 v89, v121
	v_exp_f32_e32 v90, v122
	v_exp_f32_e32 v91, v123
	v_exp_f32_e32 v92, v112
	v_exp_f32_e32 v93, v113
	v_exp_f32_e32 v94, v114
	v_exp_f32_e32 v95, v115
	v_fmamk_f32 v108, v96, 0x3e0293ee, v180
	v_fmamk_f32 v182, v97, 0x3e0293ee, v180
	v_fmamk_f32 v183, v98, 0x3e0293ee, v180
	v_fmac_f32_e32 v180, 0x3e0293ee, v99
	s_waitcnt lgkmcnt(0)
	s_barrier
	v_mov_b32_e32 v96, v200
	v_exp_f32_e32 v101, v101
	v_add_u32_e32 v96, 0, v96
	v_add_u32_e32 v96, 0x10800, v96
	ds_read_b128 v[128:131], v96
	ds_read_b128 v[132:135], v96 offset:32
	ds_read_b128 v[112:115], v96 offset:128
	ds_read_b128 v[116:119], v96 offset:160
	ds_read_b128 v[136:139], v96 offset:64
	ds_read_b128 v[120:123], v96 offset:192
	ds_read_b128 v[140:143], v96 offset:96
	ds_read_b128 v[124:127], v96 offset:224
	ds_read_b128 v[96:99], v233 offset:32768
	ds_read_b128 v[184:187], v233 offset:40960
	v_exp_f32_e32 v102, v102
	v_exp_f32_e32 v103, v103
	s_waitcnt lgkmcnt(1)
	s_waitcnt lgkmcnt(1)
	v_mfma_f32_32x32x16_bf16 v[128:143], v[96:99], v[172:175], v[128:143]
	ds_read_b128 v[96:99], v234 offset:32768
	v_exp_f32_e32 v104, v104
	v_exp_f32_e32 v105, v105
	v_exp_f32_e32 v106, v106
	v_exp_f32_e32 v107, v107
	v_exp_f32_e32 v108, v108
	s_waitcnt lgkmcnt(1)
	v_mfma_f32_32x32x16_bf16 v[112:127], v[184:187], v[172:175], v[112:127]
	ds_read_b128 v[184:187], v234 offset:40960
	s_waitcnt lgkmcnt(1)
	v_mfma_f32_32x32x16_bf16 v[128:143], v[96:99], v[168:171], v[128:143]
	ds_read_b128 v[96:99], v232 offset:32768
	s_waitcnt lgkmcnt(1)
	v_mfma_f32_32x32x16_bf16 v[112:127], v[184:187], v[168:171], v[112:127]
	ds_read_b128 v[184:187], v232 offset:40960
	s_waitcnt lgkmcnt(1)
	v_mfma_f32_32x32x16_bf16 v[128:143], v[96:99], v[164:167], v[128:143]
	ds_read_b128 v[96:99], v230 offset:32768
	s_waitcnt lgkmcnt(1)
	v_mfma_f32_32x32x16_bf16 v[112:127], v[184:187], v[164:167], v[112:127]
	ds_read_b128 v[184:187], v230 offset:40960
	s_waitcnt lgkmcnt(1)
	v_mfma_f32_32x32x16_bf16 v[128:143], v[96:99], v[160:163], v[128:143]
	ds_read_b128 v[96:99], v233 offset:32896
	s_waitcnt lgkmcnt(1)
	v_mfma_f32_32x32x16_bf16 v[112:127], v[184:187], v[160:163], v[112:127]
	ds_read_b128 v[184:187], v233 offset:41088
	s_waitcnt lgkmcnt(1)
	v_mfma_f32_32x32x16_bf16 v[128:143], v[96:99], v[156:159], v[128:143]
	ds_read_b128 v[96:99], v234 offset:32896
	s_waitcnt lgkmcnt(1)
	v_mfma_f32_32x32x16_bf16 v[112:127], v[184:187], v[156:159], v[112:127]
	ds_read_b128 v[184:187], v234 offset:41088
	s_waitcnt lgkmcnt(1)
	v_mfma_f32_32x32x16_bf16 v[128:143], v[96:99], v[152:155], v[128:143]
	ds_read_b128 v[96:99], v232 offset:32896
	s_waitcnt lgkmcnt(1)
	v_mfma_f32_32x32x16_bf16 v[112:127], v[184:187], v[152:155], v[112:127]
	ds_read_b128 v[184:187], v232 offset:41088
	s_waitcnt lgkmcnt(1)
	v_mfma_f32_32x32x16_bf16 v[128:143], v[96:99], v[148:151], v[128:143]
	ds_read_b128 v[96:99], v230 offset:32896
	s_waitcnt lgkmcnt(1)
	v_mfma_f32_32x32x16_bf16 v[112:127], v[184:187], v[148:151], v[112:127]
	ds_read_b128 v[184:187], v230 offset:41088
	s_waitcnt lgkmcnt(1)
	v_mfma_f32_32x32x16_bf16 v[128:143], v[96:99], v[144:147], v[128:143]
	v_exp_f32_e32 v99, v111
	v_exp_f32_e32 v111, v180
	v_add_f32_e32 v180, 0, v80
	v_add_f32_e32 v180, v81, v180
	v_add_f32_e32 v180, v82, v180
	v_add_f32_e32 v180, v83, v180
	v_add_f32_e32 v180, v84, v180
	v_add_f32_e32 v180, v85, v180
	v_add_f32_e32 v180, v86, v180
	v_add_f32_e32 v180, v87, v180
	v_add_f32_e32 v180, v88, v180
	v_add_f32_e32 v180, v89, v180
	v_add_f32_e32 v180, v90, v180
	v_add_f32_e32 v180, v91, v180
	v_exp_f32_e32 v96, v100
	v_add_f32_e32 v180, v92, v180
	v_exp_f32_e32 v97, v109
	v_add_f32_e32 v180, v93, v180
	v_exp_f32_e32 v98, v110
	v_add_f32_e32 v180, v94, v180
	v_add_f32_e32 v180, v95, v180
	v_exp_f32_e32 v100, v181
	v_add_f32_e32 v180, v96, v180
	v_add_f32_e32 v180, v97, v180
	v_add_f32_e32 v180, v98, v180
	v_add_f32_e32 v180, v99, v180
	v_add_f32_e32 v180, v100, v180
	v_add_f32_e32 v180, v101, v180
	v_add_f32_e32 v180, v102, v180
	v_add_f32_e32 v180, v103, v180
	v_add_f32_e32 v180, v104, v180
	v_exp_f32_e32 v109, v182
	v_add_f32_e32 v180, v105, v180
	s_waitcnt lgkmcnt(0)
	v_mfma_f32_32x32x16_bf16 v[112:127], v[184:187], v[144:147], v[112:127]
	v_exp_f32_e32 v110, v183
	v_add_f32_e32 v180, v106, v180
	v_add_f32_e32 v180, v107, v180
	v_add_f32_e32 v180, v108, v180
	v_add_f32_e32 v180, v109, v180
	v_add_f32_e32 v180, v110, v180
	v_add_f32_e32 v242, v111, v180
	v_mov_b32_e32 v243, v242
	v_cvt_pk_bf16_f32 v180, v80, v81
	v_cvt_pk_bf16_f32 v181, v82, v83
	v_cvt_pk_bf16_f32 v182, v84, v85
	v_cvt_pk_bf16_f32 v183, v86, v87
	v_cvt_pk_bf16_f32 v184, v88, v89
	v_cvt_pk_bf16_f32 v185, v90, v91
	v_cvt_pk_bf16_f32 v186, v92, v93
	v_cvt_pk_bf16_f32 v187, v94, v95
	v_cvt_pk_bf16_f32 v188, v96, v97
	v_cvt_pk_bf16_f32 v189, v98, v99
	v_cvt_pk_bf16_f32 v190, v100, v101
	v_cvt_pk_bf16_f32 v191, v102, v103
	v_cvt_pk_bf16_f32 v192, v104, v105
	v_cvt_pk_bf16_f32 v193, v106, v107
	v_cvt_pk_bf16_f32 v194, v108, v109
	v_cvt_pk_bf16_f32 v195, v110, v111
	s_nop 1
	v_permlane32_swap_b32_e32 v242, v243
	v_permlane32_swap_b32_e32 v180, v182
	v_permlane32_swap_b32_e32 v181, v183
	v_permlane32_swap_b32_e32 v184, v186
	v_permlane32_swap_b32_e32 v185, v187
	v_permlane32_swap_b32_e32 v188, v190
	v_permlane32_swap_b32_e32 v189, v191
	v_permlane32_swap_b32_e32 v192, v194
	v_permlane32_swap_b32_e32 v193, v195
	s_add_i32 s8, s46, 1
	v_cmp_lt_i32_e64 s[8:9], s8, v235
	s_and_saveexec_b64 s[60:61], s[8:9]
	s_cbranch_execz .LBB0_227
	v_add_u32_e32 v4, 32, v210
	v_ashrrev_i32_e32 v211, 31, v210
	v_ashrrev_i32_e32 v5, 31, v4
	v_lshlrev_b64 v[10:11], 11, v[210:211]
	v_lshlrev_b64 v[12:13], 11, v[4:5]
	v_lshl_add_u64 v[2:3], v[14:15], 0, v[10:11]
	v_lshl_add_u64 v[6:7], v[14:15], 0, v[12:13]
	v_lshl_add_u64 v[10:11], v[206:207], 0, v[10:11]
	v_lshl_add_u64 v[176:177], v[206:207], 0, v[12:13]
	flat_load_dwordx4 v[2:5], v[2:3]
	s_nop 0
	flat_load_dwordx4 v[6:9], v[6:7]
	s_nop 0
	flat_load_dwordx4 v[10:13], v[10:11]
	s_nop 0
	flat_load_dwordx4 v[176:179], v[176:177]
	s_and_b64 vcc, exec, s[6:7]
	s_cbranch_vccnz .LBB0_226
	s_ashr_i32 s91, s90, 31
	s_mov_b64 s[6:7], src_shared_base
	s_cmp_lg_u32 0, -1
	s_cselect_b32 s6, 0, 0
	s_cselect_b32 s7, s7, 0
	s_add_u32 s6, s6, 0x10800
	s_addc_u32 s7, s7, 0
	s_cmp_lg_u64 s[6:7], 0
	s_cselect_b32 s6, s6, -1
	v_lshl_add_u64 v[196:197], s[90:91], 2, v[208:209]
	s_add_i32 m0, s6, 0x100
	s_nop 0
	global_load_lds_dword v[196:197], off
; DEVI void mask_tile(f32x16& p0, f32x16& p1, int dq, unsigned W) {
;     const float NEG = -__builtin_inff();
; #pragma unroll
;     for (int r = 0; r < 16; ++r) {
;         const int c = (r & 3) + 8 * (r >> 2);
;         if ((unsigned)(dq - c) >= W) p0[r] = NEG;
;         if ((unsigned)(dq - c - 32) >= W) p1[r] = NEG;
;     }
; }
; template <int VB>
; DEVI void pv_tile(f32x16* o, int vb0, bf16x8 pa0, bf16x8 pa1, bf16x8 pa2, bf16x8 pa3) {
;     ...
;     PV_D0(0); PV_D0(1); PV_D0(2); PV_D0(3);
.LBB0_226:
.LBB0_227:
	s_or_b64 exec, exec, s[60:61]
	ds_read_b64_tr_b16 v[210:211], v227 offset:0x4000
	ds_read_b64_tr_b16 v[212:213], v227 offset:0x4800
	ds_read_b64_tr_b16 v[244:245], v227 offset:0x5000
	ds_read_b64_tr_b16 v[246:247], v227 offset:0x5800
	ds_read_b64_tr_b16 v[248:249], v227 offset:0x6000
	ds_read_b64_tr_b16 v[250:251], v227 offset:0x6800
	ds_read_b64_tr_b16 v[196:197], v227 offset:0x7000
	ds_read_b64_tr_b16 v[198:199], v227 offset:0x7800
	s_nop 0
	s_nop 0
	s_waitcnt lgkmcnt(6)
	v_mfma_f32_32x32x16_bf16 v[64:79], v[180:183], v[210:213], v[64:79]
	s_waitcnt lgkmcnt(4)
	v_mfma_f32_32x32x16_bf16 v[64:79], v[184:187], v[244:247], v[64:79]
	s_waitcnt lgkmcnt(2)
	v_mfma_f32_32x32x16_bf16 v[64:79], v[188:191], v[248:251], v[64:79]
	s_waitcnt lgkmcnt(0)
	v_mfma_f32_32x32x16_bf16 v[64:79], v[192:195], v[196:199], v[64:79]
	ds_read_b64_tr_b16 v[196:197], v227 offset:0x4200
	ds_read_b64_tr_b16 v[198:199], v227 offset:0x4a00
	ds_read_b64_tr_b16 v[210:211], v227 offset:0x5200
	ds_read_b64_tr_b16 v[212:213], v227 offset:0x5a00
	ds_read_b64_tr_b16 v[244:245], v227 offset:0x6200
	ds_read_b64_tr_b16 v[246:247], v227 offset:0x6a00
	ds_read_b64_tr_b16 v[248:249], v227 offset:0x7200
	ds_read_b64_tr_b16 v[250:251], v227 offset:0x7a00
	s_nop 0
	s_nop 0
	s_waitcnt lgkmcnt(6)
	v_mfma_f32_32x32x16_bf16 v[48:63], v[180:183], v[196:199], v[48:63]
	ds_read_b64_tr_b16 v[196:197], v227 offset:0x4400
	ds_read_b64_tr_b16 v[198:199], v227 offset:0x4c00
	s_waitcnt lgkmcnt(6)
	v_mfma_f32_32x32x16_bf16 v[48:63], v[184:187], v[210:213], v[48:63]
	ds_read_b64_tr_b16 v[210:211], v227 offset:0x5400
	ds_read_b64_tr_b16 v[212:213], v227 offset:0x5c00
	s_waitcnt lgkmcnt(6)
	v_mfma_f32_32x32x16_bf16 v[48:63], v[188:191], v[244:247], v[48:63]
	ds_read_b64_tr_b16 v[244:245], v227 offset:0x6400
	ds_read_b64_tr_b16 v[246:247], v227 offset:0x6c00
	s_waitcnt lgkmcnt(6)
	v_mfma_f32_32x32x16_bf16 v[48:63], v[192:195], v[248:251], v[48:63]
	ds_read_b64_tr_b16 v[248:249], v227 offset:0x7400
	ds_read_b64_tr_b16 v[250:251], v227 offset:0x7c00
	s_nop 0
	s_waitcnt lgkmcnt(6)
	v_mfma_f32_32x32x16_bf16 v[32:47], v[180:183], v[196:199], v[32:47]
	ds_read_b64_tr_b16 v[196:197], v227 offset:0x4600
	ds_read_b64_tr_b16 v[198:199], v227 offset:0x4e00
	s_waitcnt lgkmcnt(6)
	v_mfma_f32_32x32x16_bf16 v[32:47], v[184:187], v[210:213], v[32:47]
	ds_read_b64_tr_b16 v[210:211], v227 offset:0x5600
	ds_read_b64_tr_b16 v[212:213], v227 offset:0x5e00
	s_waitcnt lgkmcnt(6)
	v_mfma_f32_32x32x16_bf16 v[32:47], v[188:191], v[244:247], v[32:47]
	ds_read_b64_tr_b16 v[244:245], v227 offset:0x6600
	ds_read_b64_tr_b16 v[246:247], v227 offset:0x6e00
	s_waitcnt lgkmcnt(6)
	v_mfma_f32_32x32x16_bf16 v[32:47], v[192:195], v[248:251], v[32:47]
	ds_read_b64_tr_b16 v[248:249], v227 offset:0x7600
	ds_read_b64_tr_b16 v[250:251], v227 offset:0x7e00
	s_nop 0
	s_waitcnt lgkmcnt(6)
	v_mfma_f32_32x32x16_bf16 v[16:31], v[180:183], v[196:199], v[16:31]
	s_add_i32 s6, s90, 0x7f
	s_cmp_le_i32 s6, s11
	s_waitcnt lgkmcnt(4)
	v_mfma_f32_32x32x16_bf16 v[16:31], v[184:187], v[210:213], v[16:31]
	s_waitcnt lgkmcnt(2)
	v_mfma_f32_32x32x16_bf16 v[16:31], v[188:191], v[244:247], v[16:31]
	s_waitcnt lgkmcnt(0)
	v_mfma_f32_32x32x16_bf16 v[16:31], v[192:195], v[248:251], v[16:31]
	s_cbranch_scc1 .LBB0_229
	v_add_u32_e32 v180, 0x4000007b, v203
	v_cmp_gt_u32_e32 vcc, 2.0, v180
	v_add_u32_e32 v180, 0x5b, v203
	s_nop 0
	v_cndmask_b32_e32 v128, v254, v128, vcc
	v_cmp_lt_u32_e32 vcc, s55, v180
	v_add_u32_e32 v180, 0x7a, v203
	s_nop 0
	v_cndmask_b32_e32 v112, v254, v112, vcc
	v_cmp_lt_u32_e32 vcc, s55, v180
	v_add_u32_e32 v180, 0x5a, v203
	s_nop 0
	v_cndmask_b32_e32 v129, v254, v129, vcc
	v_cmp_lt_u32_e32 vcc, s55, v180
	v_add_u32_e32 v180, 0x79, v203
	s_nop 0
	v_cndmask_b32_e32 v113, v254, v113, vcc
	v_cmp_lt_u32_e32 vcc, s55, v180
	v_add_u32_e32 v180, 0x59, v203
	s_nop 0
	v_cndmask_b32_e32 v130, v254, v130, vcc
	v_cmp_lt_u32_e32 vcc, s55, v180
	v_add_u32_e32 v180, 0x78, v203
	s_nop 0
	v_cndmask_b32_e32 v114, v254, v114, vcc
	v_cmp_lt_u32_e32 vcc, s55, v180
	v_add_u32_e32 v180, 0x58, v203
	s_nop 0
	v_cndmask_b32_e32 v131, v254, v131, vcc
	v_cmp_lt_u32_e32 vcc, s55, v180
	v_add_u32_e32 v180, 0x73, v203
	s_nop 0
	v_cndmask_b32_e32 v115, v254, v115, vcc
	v_cmp_lt_u32_e32 vcc, s55, v180
	v_add_u32_e32 v180, 0x53, v203
	s_nop 0
	v_cndmask_b32_e32 v132, v254, v132, vcc
	v_cmp_lt_u32_e32 vcc, s55, v180
	v_add_u32_e32 v180, 0x72, v203
	s_nop 0
	v_cndmask_b32_e32 v116, v254, v116, vcc
	v_cmp_lt_u32_e32 vcc, s55, v180
	v_add_u32_e32 v180, 0x52, v203
	s_nop 0
	v_cndmask_b32_e32 v133, v254, v133, vcc
	v_cmp_lt_u32_e32 vcc, s55, v180
	v_add_u32_e32 v180, 0x71, v203
	s_nop 0
	v_cndmask_b32_e32 v117, v254, v117, vcc
	v_cmp_lt_u32_e32 vcc, s55, v180
	v_add_u32_e32 v180, 0x51, v203
	s_nop 0
	v_cndmask_b32_e32 v134, v254, v134, vcc
	v_cmp_lt_u32_e32 vcc, s55, v180
	v_add_u32_e32 v180, 0x70, v203
	s_nop 0
	v_cndmask_b32_e32 v118, v254, v118, vcc
	v_cmp_lt_u32_e32 vcc, s55, v180
	v_add_u32_e32 v180, 0x50, v203
	s_nop 0
	v_cndmask_b32_e32 v135, v254, v135, vcc
	v_cmp_lt_u32_e32 vcc, s55, v180
	v_add_u32_e32 v180, 0x6b, v203
	s_nop 0
	v_cndmask_b32_e32 v119, v254, v119, vcc
	v_cmp_lt_u32_e32 vcc, s55, v180
	v_add_u32_e32 v180, 0x4b, v203
	s_nop 0
	v_cndmask_b32_e32 v136, v254, v136, vcc
	v_cmp_lt_u32_e32 vcc, s55, v180
	v_add_u32_e32 v180, 0x6a, v203
	s_nop 0
	v_cndmask_b32_e32 v120, v254, v120, vcc
	v_cmp_lt_u32_e32 vcc, s55, v180
	v_add_u32_e32 v180, 0x4a, v203
	s_nop 0
	v_cndmask_b32_e32 v137, v254, v137, vcc
	v_cmp_lt_u32_e32 vcc, s55, v180
	v_add_u32_e32 v180, 0x69, v203
	s_nop 0
	v_cndmask_b32_e32 v121, v254, v121, vcc
	v_cmp_lt_u32_e32 vcc, s55, v180
	v_add_u32_e32 v180, 0x49, v203
	s_nop 0
	v_cndmask_b32_e32 v138, v254, v138, vcc
	v_cmp_lt_u32_e32 vcc, s55, v180
	v_add_u32_e32 v180, 0x68, v203
	s_nop 0
	v_cndmask_b32_e32 v122, v254, v122, vcc
	v_cmp_lt_u32_e32 vcc, s55, v180
	v_add_u32_e32 v180, 0x48, v203
	s_nop 0
	v_cndmask_b32_e32 v139, v254, v139, vcc
	v_cmp_lt_u32_e32 vcc, s55, v180
	v_add_u32_e32 v180, 0x63, v203
	s_nop 0
	v_cndmask_b32_e32 v123, v254, v123, vcc
	v_cmp_lt_u32_e32 vcc, s55, v180
	v_add_u32_e32 v180, 0x43, v203
	s_nop 0
	v_cndmask_b32_e32 v140, v254, v140, vcc
	v_cmp_lt_u32_e32 vcc, s55, v180
	v_add_u32_e32 v180, 0x62, v203
	s_nop 0
	v_cndmask_b32_e32 v124, v254, v124, vcc
	v_cmp_lt_u32_e32 vcc, s55, v180
	v_add_u32_e32 v180, 0x42, v203
	s_nop 0
	v_cndmask_b32_e32 v141, v254, v141, vcc
	v_cmp_lt_u32_e32 vcc, s55, v180
	v_add_u32_e32 v180, 0x61, v203
	s_nop 0
	v_cndmask_b32_e32 v125, v254, v125, vcc
	v_cmp_lt_u32_e32 vcc, s55, v180
	v_add_u32_e32 v180, 0x41, v203
	s_nop 0
	v_cndmask_b32_e32 v142, v254, v142, vcc
	v_cmp_lt_u32_e32 vcc, s55, v180
	v_add_u32_e32 v180, 0x60, v203
	s_nop 0
	v_cndmask_b32_e32 v126, v254, v126, vcc
	v_cmp_lt_u32_e32 vcc, s55, v180
	v_add_u32_e32 v180, 64, v203
	s_nop 0
	v_cndmask_b32_e32 v143, v254, v143, vcc
	v_cmp_lt_u32_e32 vcc, s55, v180
	s_nop 1
	v_cndmask_b32_e32 v127, v254, v127, vcc

; #define SBAR() __builtin_amdgcn_sched_barrier(0)
; DEVI void finishSM(f32x16& p0, f32x16& p1, float alpha, float& l_reg, bf16x8& pa0, bf16x8& pa1, bf16x8& pa2, bf16x8& pa3) {
;     for (int r = 0; r < 16; ++r) p1[r] = __builtin_amdgcn_exp2f(p1[r]);
;     float ps = 0; for (int r = 0; r < 16; ++r) ps += p0[r]; for (int r = 0; r < 16; ++r) ps += p1[r];
;     { auto rr = __builtin_amdgcn_permlane32_swap(__float_as_uint(ps), __float_as_uint(ps), false, false);
;       ps = __uint_as_float(rr[0]) + __uint_as_float(rr[1]); }
;     l_reg = l_reg * alpha + ps;
;     ...
;     PK4(p0, 0, pa0); PK4(p0, 8, pa1); PK4(p1, 0, pa2); PK4(p1, 8, pa3);
;     ...
; }
; template <int KB>
; DEVI void qkt(f32x16& p0, f32x16& p1, const char* K_lds, const char* biasb0, int r32, int hi, const bf16x8* qr) {
;     int hb_ = hi * 16; asm volatile("" : "+v"(hb_)); const char* biasb = biasb0 + hb_;
; #pragma unroll
;     for (int g = 0; g < 4; ++g) { const f32x4 b0 = *(const f32x4*)(biasb + KB * 256 + g * 32), b1 = *(const f32x4*)(biasb + KB * 256 + 128 + g * 32);
; #pragma unroll
;         for (int i = 0; i < 4; ++i) { p0[4 * g + i] = b0[i]; p1[4 * g + i] = b1[i]; } }
;     const char* kb[4];
; #pragma unroll
;     for (int dd = 0; dd < 4; ++dd) kb[dd] = K_lds + KB * SHM_K + KSWZ(r32, (dd * 16 + hi * 8) * 2);
; #pragma unroll
;     for (int d0 = 0; d0 < 8; ++d0) { const char* a = kb[d0 & 3] + (d0 >> 2) * 128;
;         bf16x8 b0 = *reinterpret_cast<const bf16x8*>(a);
;         bf16x8 b1 = *reinterpret_cast<const bf16x8*>(a + 32 * 256);
;         p0 = __builtin_amdgcn_mfma_f32_32x32x16_bf16(b0, qr[d0], p0, 0, 0, 0);
;         p1 = __builtin_amdgcn_mfma_f32_32x32x16_bf16(b1, qr[d0], p1, 0, 0, 0); }
; }
; template <int VB>
; DEVI void pv_tile(f32x16* o, int vb0, bf16x8 pa0, bf16x8 pa1, bf16x8 pa2, bf16x8 pa3) {
;     ...
;     PV_D0(0); PV_D0(1); PV_D0(2); PV_D0(3);
; DEVI void block(const BlockRef& cur, const BlockRef& nxt, char* lds, Seam& S, int wv) {
;     ...
;     for (int d0 = 0; d0 < 8; ++d0) S.qr[d0] = ld8(nxt.Q + (size_t)(wid * QBLK + r32) * RS + d0 * 16 + hi * 8);
;     SBAR();
;     finishSM(pA0, pA1, alA, l_reg, pa0, pa1, pa2, pa3); SBAR();
;     pv_tile<0>(o, vb0, pa0, pa1, pa2, pa3);
.LBB0_239:
	v_or_b32_e32 v2, s88, v222
	v_ashrrev_i32_e32 v3, 31, v2
	v_lshlrev_b64 v[2:3], 11, v[2:3]
	v_lshl_add_u64 v[2:3], s[18:19], 0, v[2:3]
	v_mov_b32_e32 v201, v1
	v_lshl_add_u64 v[2:3], v[2:3], 0, v[200:201]
	flat_load_dwordx4 v[172:175], v[2:3]
	flat_load_dwordx4 v[168:171], v[2:3] offset:32
	flat_load_dwordx4 v[164:167], v[2:3] offset:64
	flat_load_dwordx4 v[160:163], v[2:3] offset:96
	flat_load_dwordx4 v[156:159], v[2:3] offset:128
	flat_load_dwordx4 v[152:155], v[2:3] offset:160
	flat_load_dwordx4 v[148:151], v[2:3] offset:192
	flat_load_dwordx4 v[144:147], v[2:3] offset:224
	v_add_f32_e32 v2, 0, v190
	v_add_f32_e32 v2, v192, v2
	v_add_f32_e32 v2, v188, v2
	v_add_f32_e32 v2, v191, v2
	v_add_f32_e32 v2, v187, v2
	v_add_f32_e32 v2, v189, v2
	v_add_f32_e32 v2, v185, v2
	v_add_f32_e32 v2, v186, v2
	v_add_f32_e32 v2, v181, v2
	v_add_f32_e32 v2, v184, v2
	v_add_f32_e32 v2, v178, v2
	v_add_f32_e32 v2, v182, v2
	v_exp_f32_e32 v3, v142
	v_add_f32_e32 v2, v176, v2
	v_exp_f32_e32 v12, v143
	v_add_f32_e32 v2, v183, v2
	v_exp_f32_e32 v13, v140
	v_add_f32_e32 v2, v177, v2
	v_exp_f32_e32 v14, v141
	v_add_f32_e32 v2, v179, v2
	v_exp_f32_e32 v15, v138
	v_add_f32_e32 v2, v3, v2
	v_exp_f32_e32 v138, v139
	v_add_f32_e32 v2, v12, v2
	v_exp_f32_e32 v136, v136
	v_add_f32_e32 v2, v13, v2
	v_exp_f32_e32 v137, v137
	v_add_f32_e32 v2, v14, v2
	v_exp_f32_e32 v134, v134
	v_add_f32_e32 v2, v15, v2
	v_exp_f32_e32 v135, v135
	v_add_f32_e32 v2, v138, v2
	v_exp_f32_e32 v132, v132
	v_add_f32_e32 v2, v136, v2
	v_exp_f32_e32 v133, v133
	v_add_f32_e32 v2, v137, v2
	v_exp_f32_e32 v130, v130
	v_add_f32_e32 v2, v134, v2
	v_exp_f32_e32 v131, v131
	v_add_f32_e32 v2, v135, v2
	v_exp_f32_e32 v139, v128
	v_add_f32_e32 v2, v132, v2
	v_exp_f32_e32 v140, v129
	v_add_f32_e32 v2, v133, v2
	v_add_f32_e32 v2, v130, v2
	v_add_f32_e32 v2, v131, v2
	v_add_f32_e32 v2, v139, v2
	v_add_f32_e32 v2, v140, v2
	v_mov_b32_e32 v4, v2
	s_nop 1
	v_permlane32_swap_b32_e32 v2, v4
	v_add_f32_e32 v2, v2, v4
	v_fmac_f32_e32 v2, v0, v238
	v_cvt_pk_bf16_f32 v4, v190, v192
	v_cvt_pk_bf16_f32 v5, v188, v191
	v_cvt_pk_bf16_f32 v6, v187, v189
	v_cvt_pk_bf16_f32 v7, v185, v186
	v_cvt_pk_bf16_f32 v8, v181, v184
	v_cvt_pk_bf16_f32 v9, v178, v182
	v_cvt_pk_bf16_f32 v10, v176, v183
	v_cvt_pk_bf16_f32 v11, v177, v179
	v_cvt_pk_bf16_f32 v12, v3, v12
	v_cvt_pk_bf16_f32 v13, v13, v14
	v_cvt_pk_bf16_f32 v14, v15, v138
	v_cvt_pk_bf16_f32 v15, v136, v137
	v_cvt_pk_bf16_f32 v128, v134, v135
	v_cvt_pk_bf16_f32 v129, v132, v133
	v_cvt_pk_bf16_f32 v130, v130, v131
	v_cvt_pk_bf16_f32 v131, v139, v140
	s_nop 0
	v_permlane32_swap_b32_e32 v4, v6
	v_permlane32_swap_b32_e32 v5, v7
	v_permlane32_swap_b32_e32 v8, v10
	v_permlane32_swap_b32_e32 v9, v11
	v_permlane32_swap_b32_e32 v12, v14
	v_permlane32_swap_b32_e32 v13, v15
	v_permlane32_swap_b32_e32 v128, v130
	v_permlane32_swap_b32_e32 v129, v131
	ds_read_b64_tr_b16 v[132:133], v227 offset:0
	ds_read_b64_tr_b16 v[134:135], v227 offset:0x800
	ds_read_b64_tr_b16 v[136:137], v227 offset:0x1000
	ds_read_b64_tr_b16 v[138:139], v227 offset:0x1800
	ds_read_b64_tr_b16 v[140:141], v227 offset:0x2000
	ds_read_b64_tr_b16 v[142:143], v227 offset:0x2800
	ds_read_b64_tr_b16 v[176:177], v227 offset:0x3000
	ds_read_b64_tr_b16 v[178:179], v227 offset:0x3800
	s_nop 0
	s_nop 0
	s_waitcnt lgkmcnt(6)
	v_mfma_f32_32x32x16_bf16 v[64:79], v[4:7], v[132:135], v[64:79]
	ds_read_b64_tr_b16 v[132:133], v227 offset:0x200
	ds_read_b64_tr_b16 v[134:135], v227 offset:0xa00
	s_waitcnt lgkmcnt(6)
	v_mfma_f32_32x32x16_bf16 v[64:79], v[8:11], v[136:139], v[64:79]
	ds_read_b64_tr_b16 v[136:137], v227 offset:0x1200
	ds_read_b64_tr_b16 v[138:139], v227 offset:0x1a00
	s_waitcnt lgkmcnt(6)
	v_mfma_f32_32x32x16_bf16 v[64:79], v[12:15], v[140:143], v[64:79]
	ds_read_b64_tr_b16 v[140:141], v227 offset:0x2200
	ds_read_b64_tr_b16 v[142:143], v227 offset:0x2a00
	s_waitcnt lgkmcnt(6)
	v_mfma_f32_32x32x16_bf16 v[64:79], v[128:131], v[176:179], v[64:79]
	ds_read_b64_tr_b16 v[176:177], v227 offset:0x3200
	ds_read_b64_tr_b16 v[178:179], v227 offset:0x3a00
	s_nop 0
	s_waitcnt lgkmcnt(6)
	v_mfma_f32_32x32x16_bf16 v[48:63], v[4:7], v[132:135], v[48:63]
	ds_read_b64_tr_b16 v[132:133], v227 offset:0x400
	ds_read_b64_tr_b16 v[134:135], v227 offset:0xc00
	s_waitcnt lgkmcnt(6)
	v_mfma_f32_32x32x16_bf16 v[48:63], v[8:11], v[136:139], v[48:63]
	ds_read_b64_tr_b16 v[136:137], v227 offset:0x1400
	ds_read_b64_tr_b16 v[138:139], v227 offset:0x1c00
	s_waitcnt lgkmcnt(6)
	v_mfma_f32_32x32x16_bf16 v[48:63], v[12:15], v[140:143], v[48:63]
	ds_read_b64_tr_b16 v[140:141], v227 offset:0x2400
	ds_read_b64_tr_b16 v[142:143], v227 offset:0x2c00
	s_waitcnt lgkmcnt(6)
	v_mfma_f32_32x32x16_bf16 v[48:63], v[128:131], v[176:179], v[48:63]
	ds_read_b64_tr_b16 v[176:177], v227 offset:0x3400
	ds_read_b64_tr_b16 v[178:179], v227 offset:0x3c00
	s_nop 0
	s_waitcnt lgkmcnt(6)
	v_mfma_f32_32x32x16_bf16 v[32:47], v[4:7], v[132:135], v[32:47]
	ds_read_b64_tr_b16 v[132:133], v227 offset:0x600
	ds_read_b64_tr_b16 v[134:135], v227 offset:0xe00
	s_waitcnt lgkmcnt(6)
	v_mfma_f32_32x32x16_bf16 v[32:47], v[8:11], v[136:139], v[32:47]
	ds_read_b64_tr_b16 v[136:137], v227 offset:0x1600
	ds_read_b64_tr_b16 v[138:139], v227 offset:0x1e00
	s_waitcnt lgkmcnt(6)
	v_mfma_f32_32x32x16_bf16 v[32:47], v[12:15], v[140:143], v[32:47]
	ds_read_b64_tr_b16 v[140:141], v227 offset:0x2600
	ds_read_b64_tr_b16 v[142:143], v227 offset:0x2e00
	s_waitcnt lgkmcnt(6)
	v_mfma_f32_32x32x16_bf16 v[32:47], v[128:131], v[176:179], v[32:47]
	ds_read_b64_tr_b16 v[176:177], v227 offset:0x3600
	ds_read_b64_tr_b16 v[178:179], v227 offset:0x3e00
	s_nop 0
	s_waitcnt lgkmcnt(6)
	v_mfma_f32_32x32x16_bf16 v[16:31], v[4:7], v[132:135], v[16:31]
	s_waitcnt lgkmcnt(4)
	v_mfma_f32_32x32x16_bf16 v[16:31], v[8:11], v[136:139], v[16:31]
	s_waitcnt lgkmcnt(2)
	v_mfma_f32_32x32x16_bf16 v[16:31], v[12:15], v[140:143], v[16:31]
	s_waitcnt lgkmcnt(0)
	v_mfma_f32_32x32x16_bf16 v[16:31], v[128:131], v[176:179], v[16:31]
	s_and_saveexec_b64 s[6:7], vcc
	s_cbranch_execz .LBB0_247
; DEVI void mask_tile(f32x16& p0, f32x16& p1, int dq, unsigned W) {
;     const float NEG = -__builtin_inff();
; #pragma unroll
;     for (int r = 0; r < 16; ++r) {
;         const int c = (r & 3) + 8 * (r >> 2);
;         if ((unsigned)(dq - c) >= W) p0[r] = NEG;
;         if ((unsigned)(dq - c - 32) >= W) p1[r] = NEG;
;     }
; }
	v_lshlrev_b32_e32 v0, 6, v223
	v_or_b32_e32 v3, 63, v0
	v_cmp_lt_i32_e32 vcc, s11, v3
	s_and_saveexec_b64 s[4:5], vcc
	s_cbranch_execz .LBB0_242
	v_sub_u32_e32 v0, v228, v0
	v_cmp_gt_u32_e32 vcc, 2.0, v0
	v_add_u32_e32 v3, 0xbfffffe0, v0
	s_nop 0
	v_cndmask_b32_e32 v80, v254, v80, vcc
	v_cmp_lt_u32_e32 vcc, s55, v3
	v_add_u32_e32 v3, 0xbfffffff, v0
	s_nop 0
	v_cndmask_b32_e32 v96, v254, v96, vcc
	v_cmp_lt_u32_e32 vcc, s55, v3
	v_add_u32_e32 v3, 0xbfffffdf, v0
	s_nop 0
	v_cndmask_b32_e32 v81, v254, v81, vcc
	v_cmp_lt_u32_e32 vcc, s55, v3
	v_add_u32_e32 v3, 0xbffffffe, v0
	s_nop 0
	v_cndmask_b32_e32 v97, v254, v97, vcc
	v_cmp_lt_u32_e32 vcc, s55, v3
	v_add_u32_e32 v3, 0xbfffffde, v0
	s_nop 0
	v_cndmask_b32_e32 v82, v254, v82, vcc
	v_cmp_lt_u32_e32 vcc, s55, v3
	v_add_u32_e32 v3, 0xbffffffd, v0
	s_nop 0
	v_cndmask_b32_e32 v98, v254, v98, vcc
	v_cmp_lt_u32_e32 vcc, s55, v3
	v_add_u32_e32 v3, 0xbfffffdd, v0
	s_nop 0
	v_cndmask_b32_e32 v83, v254, v83, vcc
	v_cmp_lt_u32_e32 vcc, s55, v3
	v_add_u32_e32 v3, 0xbffffff8, v0
	s_nop 0
	v_cndmask_b32_e32 v99, v254, v99, vcc
	v_cmp_lt_u32_e32 vcc, s55, v3
	v_add_u32_e32 v3, 0xbfffffd8, v0
	s_nop 0
	v_cndmask_b32_e32 v84, v254, v84, vcc
	v_cmp_lt_u32_e32 vcc, s55, v3
	v_add_u32_e32 v3, 0xbffffff7, v0
	s_nop 0
	v_cndmask_b32_e32 v100, v254, v100, vcc
	v_cmp_lt_u32_e32 vcc, s55, v3
	v_add_u32_e32 v3, 0xbfffffd7, v0
	s_nop 0
	v_cndmask_b32_e32 v85, v254, v85, vcc
	v_cmp_lt_u32_e32 vcc, s55, v3
	v_add_u32_e32 v3, 0xbffffff6, v0
	s_nop 0
	v_cndmask_b32_e32 v101, v254, v101, vcc
	v_cmp_lt_u32_e32 vcc, s55, v3
	v_add_u32_e32 v3, 0xbfffffd6, v0
	s_nop 0
	v_cndmask_b32_e32 v86, v254, v86, vcc
	v_cmp_lt_u32_e32 vcc, s55, v3
	v_add_u32_e32 v3, 0xbffffff5, v0
	s_nop 0
	v_cndmask_b32_e32 v102, v254, v102, vcc
	v_cmp_lt_u32_e32 vcc, s55, v3
	v_add_u32_e32 v3, 0xbfffffd5, v0
	s_nop 0
	v_cndmask_b32_e32 v87, v254, v87, vcc
	v_cmp_lt_u32_e32 vcc, s55, v3
	v_add_u32_e32 v3, 0xbffffff0, v0
	s_nop 0
	v_cndmask_b32_e32 v103, v254, v103, vcc
	v_cmp_lt_u32_e32 vcc, s55, v3
	v_add_u32_e32 v3, 0xbfffffd0, v0
	s_nop 0
	v_cndmask_b32_e32 v88, v254, v88, vcc
	v_cmp_lt_u32_e32 vcc, s55, v3
	v_add_u32_e32 v3, 0xbfffffef, v0
	s_nop 0
	v_cndmask_b32_e32 v104, v254, v104, vcc
	v_cmp_lt_u32_e32 vcc, s55, v3
	v_add_u32_e32 v3, 0xbfffffcf, v0
	s_nop 0
	v_cndmask_b32_e32 v89, v254, v89, vcc
	v_cmp_lt_u32_e32 vcc, s55, v3
	v_add_u32_e32 v3, 0xbfffffee, v0
	s_nop 0
	v_cndmask_b32_e32 v105, v254, v105, vcc
	v_cmp_lt_u32_e32 vcc, s55, v3
	v_add_u32_e32 v3, 0xbfffffce, v0
	s_nop 0
	v_cndmask_b32_e32 v90, v254, v90, vcc
	v_cmp_lt_u32_e32 vcc, s55, v3
	v_add_u32_e32 v3, 0xbfffffed, v0
	s_nop 0
	v_cndmask_b32_e32 v106, v254, v106, vcc
	v_cmp_lt_u32_e32 vcc, s55, v3
	v_add_u32_e32 v3, 0xbfffffcd, v0
	s_nop 0
	v_cndmask_b32_e32 v91, v254, v91, vcc
	v_cmp_lt_u32_e32 vcc, s55, v3
	v_add_u32_e32 v3, 0xbfffffe8, v0
	s_nop 0
	v_cndmask_b32_e32 v107, v254, v107, vcc
	v_cmp_lt_u32_e32 vcc, s55, v3
	v_add_u32_e32 v3, 0xbfffffc8, v0
	s_nop 0
	v_cndmask_b32_e32 v92, v254, v92, vcc
	v_cmp_lt_u32_e32 vcc, s55, v3
	v_add_u32_e32 v3, 0xbfffffe7, v0
	s_nop 0
	v_cndmask_b32_e32 v108, v254, v108, vcc
	v_cmp_lt_u32_e32 vcc, s55, v3
	v_add_u32_e32 v3, 0xbfffffc7, v0
	s_nop 0
	v_cndmask_b32_e32 v93, v254, v93, vcc
	v_cmp_lt_u32_e32 vcc, s55, v3
	v_add_u32_e32 v3, 0xbfffffe6, v0
	s_nop 0
	v_cndmask_b32_e32 v109, v254, v109, vcc
	v_cmp_lt_u32_e32 vcc, s55, v3
	v_add_u32_e32 v3, 0xbfffffc6, v0
	s_nop 0
	v_cndmask_b32_e32 v94, v254, v94, vcc
	v_cmp_lt_u32_e32 vcc, s55, v3
	v_add_u32_e32 v3, 0xbfffffe5, v0
	v_add_u32_e32 v0, 0xbfffffc5, v0
	v_cndmask_b32_e32 v110, v254, v110, vcc
	v_cmp_lt_u32_e32 vcc, s55, v3
	s_nop 1
	v_cndmask_b32_e32 v95, v254, v95, vcc
	v_cmp_lt_u32_e32 vcc, s55, v0
	s_nop 1
	v_cndmask_b32_e32 v111, v254, v111, vcc

; DEVI void partialSM(f32x16& p0, f32x16& p1, float& m_reg, float& mn, float& alpha) {
;     float pmax = p0[0]; for (int r = 1; r < 16; ++r) pmax = fmaxf(pmax, p0[r]); for (int r = 0; r < 16; ++r) pmax = fmaxf(pmax, p1[r]);
;     { auto rr = __builtin_amdgcn_permlane32_swap(__float_as_uint(pmax), __float_as_uint(pmax), false, false);
;       pmax = fmaxf(__uint_as_float(rr[0]), __uint_as_float(rr[1])); }
;     constexpr float C2 = 1.4426950408889634f * SCALE;
;     if (__builtin_expect(__all((pmax - m_reg) * SCALE <= THR), 1)) { mn = m_reg; alpha = 1.f; }
;     else { mn = fmaxf(m_reg, pmax); alpha = __builtin_amdgcn_exp2f((m_reg - mn) * C2); m_reg = mn; }
;     const float mnL = -mn * C2;
;     for (int r = 0; r < 16; ++r) p0[r] = fmaf(p0[r], C2, mnL); for (int r = 0; r < 16; ++r) p1[r] = fmaf(p1[r], C2, mnL);
;     for (int r = 0; r < 16; ++r) p0[r] = __builtin_amdgcn_exp2f(p0[r]);
; }
; DEVI void finishSM(f32x16& p0, f32x16& p1, float alpha, float& l_reg, bf16x8& pa0, bf16x8& pa1, bf16x8& pa2, bf16x8& pa3) {
;     for (int r = 0; r < 16; ++r) p1[r] = __builtin_amdgcn_exp2f(p1[r]);
;     float ps = 0; for (int r = 0; r < 16; ++r) ps += p0[r]; for (int r = 0; r < 16; ++r) ps += p1[r];
;     { auto rr = __builtin_amdgcn_permlane32_swap(__float_as_uint(ps), __float_as_uint(ps), false, false);
;       ps = __uint_as_float(rr[0]) + __uint_as_float(rr[1]); }
;     l_reg = l_reg * alpha + ps;
;     ...
;     PK4(p0, 0, pa0); PK4(p0, 8, pa1); PK4(p1, 0, pa2); PK4(p1, 8, pa3);
;     ...
; }
; template <int KB>
; DEVI void qkt(f32x16& p0, f32x16& p1, const char* K_lds, const char* biasb0, int r32, int hi, const bf16x8* qr) {
;     int hb_ = hi * 16; asm volatile("" : "+v"(hb_)); const char* biasb = biasb0 + hb_;
; #pragma unroll
;     for (int g = 0; g < 4; ++g) { const f32x4 b0 = *(const f32x4*)(biasb + KB * 256 + g * 32), b1 = *(const f32x4*)(biasb + KB * 256 + 128 + g * 32);
; #pragma unroll
;         for (int i = 0; i < 4; ++i) { p0[4 * g + i] = b0[i]; p1[4 * g + i] = b1[i]; } }
;     const char* kb[4];
; #pragma unroll
;     for (int dd = 0; dd < 4; ++dd) kb[dd] = K_lds + KB * SHM_K + KSWZ(r32, (dd * 16 + hi * 8) * 2);
; #pragma unroll
;     for (int d0 = 0; d0 < 8; ++d0) { const char* a = kb[d0 & 3] + (d0 >> 2) * 128;
;         bf16x8 b0 = *reinterpret_cast<const bf16x8*>(a);
;         bf16x8 b1 = *reinterpret_cast<const bf16x8*>(a + 32 * 256);
.LBB0_246:
	v_cndmask_b32_e64 v3, v3, v180, s[4:5]
	v_mul_f32_e32 v128, 0xbe0293ee, v3
	v_fmamk_f32 v3, v80, 0x3e0293ee, v128
	v_fmamk_f32 v4, v81, 0x3e0293ee, v128
	v_exp_f32_e32 v80, v3
	v_fmamk_f32 v5, v82, 0x3e0293ee, v128
	v_exp_f32_e32 v82, v4
	v_fmamk_f32 v6, v83, 0x3e0293ee, v128
	v_exp_f32_e32 v14, v5
	v_fmamk_f32 v7, v84, 0x3e0293ee, v128
	v_fmamk_f32 v83, v96, 0x3e0293ee, v128
	v_exp_f32_e32 v81, v6
	v_fmamk_f32 v8, v85, 0x3e0293ee, v128
	v_fmamk_f32 v85, v98, 0x3e0293ee, v128
	v_exp_f32_e32 v12, v7
	v_exp_f32_e32 v98, v83
	v_add_f32_e32 v83, 0, v80
	v_fmamk_f32 v9, v86, 0x3e0293ee, v128
	v_exp_f32_e32 v15, v8
	v_add_f32_e32 v83, v82, v83
	v_fmamk_f32 v10, v87, 0x3e0293ee, v128
	v_exp_f32_e32 v11, v9
	v_add_f32_e32 v83, v14, v83
	v_fmamk_f32 v129, v88, 0x3e0293ee, v128
	v_exp_f32_e32 v13, v10
	v_add_f32_e32 v83, v81, v83
	v_fmamk_f32 v130, v89, 0x3e0293ee, v128
	v_exp_f32_e32 v8, v129
	v_add_f32_e32 v83, v12, v83
	v_fmamk_f32 v131, v90, 0x3e0293ee, v128
	v_exp_f32_e32 v10, v130
	v_add_f32_e32 v83, v15, v83
	v_fmamk_f32 v132, v91, 0x3e0293ee, v128
	v_exp_f32_e32 v6, v131
	v_add_f32_e32 v83, v11, v83
	v_fmamk_f32 v133, v92, 0x3e0293ee, v128
	v_exp_f32_e32 v9, v132
	v_add_f32_e32 v83, v13, v83
	v_fmamk_f32 v134, v93, 0x3e0293ee, v128
	v_exp_f32_e32 v4, v133
	v_add_f32_e32 v83, v8, v83
	v_fmamk_f32 v135, v94, 0x3e0293ee, v128
	v_exp_f32_e32 v7, v134
	v_add_f32_e32 v83, v10, v83
	v_fmamk_f32 v136, v95, 0x3e0293ee, v128
	v_exp_f32_e32 v3, v135
	v_add_f32_e32 v83, v6, v83
	v_exp_f32_e32 v5, v136
	v_add_f32_e32 v83, v9, v83
	v_fmamk_f32 v84, v97, 0x3e0293ee, v128
	v_add_f32_e32 v83, v4, v83
	v_exp_f32_e32 v84, v84
	v_add_f32_e32 v83, v7, v83
	v_fmamk_f32 v86, v99, 0x3e0293ee, v128
	v_exp_f32_e32 v85, v85
	v_add_f32_e32 v83, v3, v83
	v_fmamk_f32 v87, v100, 0x3e0293ee, v128
	v_exp_f32_e32 v86, v86
	v_add_f32_e32 v83, v5, v83
	v_fmamk_f32 v88, v101, 0x3e0293ee, v128
	v_exp_f32_e32 v87, v87
	v_add_f32_e32 v83, v98, v83
	v_fmamk_f32 v89, v102, 0x3e0293ee, v128
	v_exp_f32_e32 v88, v88
	v_add_f32_e32 v83, v84, v83
	v_fmamk_f32 v90, v103, 0x3e0293ee, v128
	v_exp_f32_e32 v89, v89
	v_add_f32_e32 v83, v85, v83
	v_fmamk_f32 v91, v104, 0x3e0293ee, v128
	v_exp_f32_e32 v90, v90
	v_add_f32_e32 v83, v86, v83
	v_fmamk_f32 v92, v105, 0x3e0293ee, v128
	v_exp_f32_e32 v91, v91
	v_add_f32_e32 v83, v87, v83
	v_fmamk_f32 v93, v106, 0x3e0293ee, v128
	v_exp_f32_e32 v92, v92
	v_add_f32_e32 v83, v88, v83
	v_fmamk_f32 v94, v107, 0x3e0293ee, v128
	v_exp_f32_e32 v93, v93
	v_add_f32_e32 v83, v89, v83
	v_fmamk_f32 v95, v108, 0x3e0293ee, v128
	v_exp_f32_e32 v94, v94
	v_add_f32_e32 v83, v90, v83
	v_fmamk_f32 v96, v109, 0x3e0293ee, v128
	v_exp_f32_e32 v95, v95
	v_add_f32_e32 v83, v91, v83
	v_fmamk_f32 v97, v110, 0x3e0293ee, v128
	v_exp_f32_e32 v96, v96
	v_add_f32_e32 v83, v92, v83
	v_fmac_f32_e32 v128, 0x3e0293ee, v111
	v_exp_f32_e32 v97, v97
	v_add_f32_e32 v83, v93, v83
	v_exp_f32_e32 v99, v128
	v_add_f32_e32 v83, v94, v83
	v_add_f32_e32 v83, v95, v83
	v_add_f32_e32 v83, v96, v83
	v_add_f32_e32 v83, v97, v83
	v_add_f32_e32 v83, v99, v83
	v_mov_b32_e32 v100, v83
	s_nop 1
	v_permlane32_swap_b32_e32 v83, v100
	v_add_f32_e32 v100, v83, v100
	v_fmac_f32_e32 v100, v2, v0
	v_cvt_pk_bf16_f32 v80, v80, v82
	v_cvt_pk_bf16_f32 v81, v14, v81
	v_cvt_pk_bf16_f32 v82, v12, v15
	v_cvt_pk_bf16_f32 v83, v11, v13
	v_cvt_pk_bf16_f32 v8, v8, v10
	v_cvt_pk_bf16_f32 v9, v6, v9
	v_cvt_pk_bf16_f32 v10, v4, v7
	v_cvt_pk_bf16_f32 v11, v3, v5
	v_cvt_pk_bf16_f32 v2, v98, v84
	v_cvt_pk_bf16_f32 v3, v85, v86
	v_cvt_pk_bf16_f32 v4, v87, v88
	v_cvt_pk_bf16_f32 v5, v89, v90
	v_cvt_pk_bf16_f32 v12, v91, v92
	v_cvt_pk_bf16_f32 v13, v93, v94
	v_cvt_pk_bf16_f32 v14, v95, v96
	v_cvt_pk_bf16_f32 v15, v97, v99
	s_nop 0
	v_permlane32_swap_b32_e32 v2, v4
	v_permlane32_swap_b32_e32 v80, v82
	v_permlane32_swap_b32_e32 v81, v83
	v_permlane32_swap_b32_e32 v8, v10
	v_permlane32_swap_b32_e32 v9, v11
	v_permlane32_swap_b32_e32 v3, v5
	v_permlane32_swap_b32_e32 v12, v14
	v_permlane32_swap_b32_e32 v13, v15
	ds_read_b64_tr_b16 v[84:85], v227 offset:0x4000
	ds_read_b64_tr_b16 v[86:87], v227 offset:0x4800
	ds_read_b64_tr_b16 v[88:89], v227 offset:0x5000
	ds_read_b64_tr_b16 v[90:91], v227 offset:0x5800
	ds_read_b64_tr_b16 v[92:93], v227 offset:0x6000
	ds_read_b64_tr_b16 v[94:95], v227 offset:0x6800
	ds_read_b64_tr_b16 v[96:97], v227 offset:0x7000
	ds_read_b64_tr_b16 v[98:99], v227 offset:0x7800
	s_nop 0
	s_nop 0
	s_waitcnt lgkmcnt(6)
	v_mfma_f32_32x32x16_bf16 v[64:79], v[80:83], v[84:87], v[64:79]
	ds_read_b64_tr_b16 v[84:85], v227 offset:0x4200
	ds_read_b64_tr_b16 v[86:87], v227 offset:0x4a00
	s_waitcnt lgkmcnt(6)
	v_mfma_f32_32x32x16_bf16 v[64:79], v[8:11], v[88:91], v[64:79]
	ds_read_b64_tr_b16 v[88:89], v227 offset:0x5200
	ds_read_b64_tr_b16 v[90:91], v227 offset:0x5a00
	s_waitcnt lgkmcnt(6)
	v_mfma_f32_32x32x16_bf16 v[64:79], v[2:5], v[92:95], v[64:79]
	ds_read_b64_tr_b16 v[92:93], v227 offset:0x6200
	ds_read_b64_tr_b16 v[94:95], v227 offset:0x6a00
	s_waitcnt lgkmcnt(6)
	v_mfma_f32_32x32x16_bf16 v[64:79], v[12:15], v[96:99], v[64:79]
	ds_read_b64_tr_b16 v[96:97], v227 offset:0x7200
	ds_read_b64_tr_b16 v[98:99], v227 offset:0x7a00
	s_nop 0
	s_waitcnt lgkmcnt(6)
	v_mfma_f32_32x32x16_bf16 v[48:63], v[80:83], v[84:87], v[48:63]
	ds_read_b64_tr_b16 v[84:85], v227 offset:0x4400
	ds_read_b64_tr_b16 v[86:87], v227 offset:0x4c00
	s_waitcnt lgkmcnt(6)
	v_mfma_f32_32x32x16_bf16 v[48:63], v[8:11], v[88:91], v[48:63]
	ds_read_b64_tr_b16 v[88:89], v227 offset:0x5400
	ds_read_b64_tr_b16 v[90:91], v227 offset:0x5c00
	s_waitcnt lgkmcnt(6)
	v_mfma_f32_32x32x16_bf16 v[48:63], v[2:5], v[92:95], v[48:63]
	ds_read_b64_tr_b16 v[92:93], v227 offset:0x6400
	ds_read_b64_tr_b16 v[94:95], v227 offset:0x6c00
	s_waitcnt lgkmcnt(6)
	v_mfma_f32_32x32x16_bf16 v[48:63], v[12:15], v[96:99], v[48:63]
	ds_read_b64_tr_b16 v[96:97], v227 offset:0x7400
	ds_read_b64_tr_b16 v[98:99], v227 offset:0x7c00
	s_nop 0
	s_waitcnt lgkmcnt(6)
	v_mfma_f32_32x32x16_bf16 v[32:47], v[80:83], v[84:87], v[32:47]
	ds_read_b64_tr_b16 v[84:85], v227 offset:0x4600
	ds_read_b64_tr_b16 v[86:87], v227 offset:0x4e00
	s_waitcnt lgkmcnt(6)
	v_mfma_f32_32x32x16_bf16 v[32:47], v[8:11], v[88:91], v[32:47]
	ds_read_b64_tr_b16 v[88:89], v227 offset:0x5600
	ds_read_b64_tr_b16 v[90:91], v227 offset:0x5e00
	s_waitcnt lgkmcnt(6)
	v_mfma_f32_32x32x16_bf16 v[32:47], v[2:5], v[92:95], v[32:47]
	ds_read_b64_tr_b16 v[92:93], v227 offset:0x6600
	ds_read_b64_tr_b16 v[94:95], v227 offset:0x6e00
	s_waitcnt lgkmcnt(6)
	v_mfma_f32_32x32x16_bf16 v[32:47], v[12:15], v[96:99], v[32:47]
	ds_read_b64_tr_b16 v[96:97], v227 offset:0x7600
	ds_read_b64_tr_b16 v[98:99], v227 offset:0x7e00
	s_nop 0
	s_waitcnt lgkmcnt(6)
	v_mfma_f32_32x32x16_bf16 v[16:31], v[80:83], v[84:87], v[16:31]
	s_waitcnt lgkmcnt(4)
	v_mfma_f32_32x32x16_bf16 v[16:31], v[8:11], v[88:91], v[16:31]
	s_waitcnt lgkmcnt(2)
	v_mfma_f32_32x32x16_bf16 v[16:31], v[2:5], v[92:95], v[16:31]
	v_mov_b32_e32 v2, v100
	s_waitcnt lgkmcnt(0)
	v_mfma_f32_32x32x16_bf16 v[16:31], v[12:15], v[96:99], v[16:31]
